# adaLN silu(c) staging: the eight c loads are issued together
# baseline (speedup 1.0000x reference)
.LBB0_11:
	global_load_dword v112, v[2:3], off
	global_load_dword v113, v[2:3], off offset:2048
	v_lshl_add_u64 v[2:3], v[2:3], 0, s[6:7]
	v_lshl_add_u64 v[2:3], v[2:3], 0, s[6:7]
	global_load_dword v114, v[2:3], off
	global_load_dword v115, v[2:3], off offset:2048
	v_lshl_add_u64 v[2:3], v[2:3], 0, s[6:7]
	v_lshl_add_u64 v[2:3], v[2:3], 0, s[6:7]
	global_load_dword v116, v[2:3], off
	global_load_dword v117, v[2:3], off offset:2048
	v_lshl_add_u64 v[2:3], v[2:3], 0, s[6:7]
	v_lshl_add_u64 v[2:3], v[2:3], 0, s[6:7]
	global_load_dword v118, v[2:3], off
	global_load_dword v119, v[2:3], off offset:2048
	v_lshl_add_u64 v[2:3], v[2:3], 0, s[6:7]
	v_lshl_add_u64 v[2:3], v[2:3], 0, s[6:7]
	v_add_u32_e32 v4, 0x1000, v4
	s_waitcnt vmcnt(7)
	v_mul_f32_e32 v8, 0xbfb8aa3b, v112
	v_exp_f32_e32 v8, v8
	s_nop 0
	v_add_f32_e32 v8, 1.0, v8
	v_div_scale_f32 v9, s[10:11], v8, v8, v112
	v_rcp_f32_e32 v10, v9
	v_div_scale_f32 v11, vcc, v112, v8, v112
	v_fma_f32 v12, -v9, v10, 1.0
	v_fmac_f32_e32 v10, v12, v10
	v_mul_f32_e32 v12, v11, v10
	v_fma_f32 v13, -v9, v12, v11
	v_fmac_f32_e32 v12, v13, v10
	v_fma_f32 v9, -v9, v12, v11
	v_div_fmas_f32 v9, v9, v10, v12
	v_div_fixup_f32 v112, v9, v8, v112
	ds_write_b32 v5, v112 offset:0
	s_waitcnt vmcnt(6)
	v_mul_f32_e32 v8, 0xbfb8aa3b, v113
	v_exp_f32_e32 v8, v8
	s_nop 0
	v_add_f32_e32 v8, 1.0, v8
	v_div_scale_f32 v9, s[10:11], v8, v8, v113
	v_rcp_f32_e32 v10, v9
	v_div_scale_f32 v11, vcc, v113, v8, v113
	v_fma_f32 v12, -v9, v10, 1.0
	v_fmac_f32_e32 v10, v12, v10
	v_mul_f32_e32 v12, v11, v10
	v_fma_f32 v13, -v9, v12, v11
	v_fmac_f32_e32 v12, v13, v10
	v_fma_f32 v9, -v9, v12, v11
	v_div_fmas_f32 v9, v9, v10, v12
	v_div_fixup_f32 v113, v9, v8, v113
	ds_write_b32 v5, v113 offset:2048
	s_waitcnt vmcnt(5)
	v_mul_f32_e32 v8, 0xbfb8aa3b, v114
	v_exp_f32_e32 v8, v8
	s_nop 0
	v_add_f32_e32 v8, 1.0, v8
	v_div_scale_f32 v9, s[10:11], v8, v8, v114
	v_rcp_f32_e32 v10, v9
	v_div_scale_f32 v11, vcc, v114, v8, v114
	v_fma_f32 v12, -v9, v10, 1.0
	v_fmac_f32_e32 v10, v12, v10
	v_mul_f32_e32 v12, v11, v10
	v_fma_f32 v13, -v9, v12, v11
	v_fmac_f32_e32 v12, v13, v10
	v_fma_f32 v9, -v9, v12, v11
	v_div_fmas_f32 v9, v9, v10, v12
	v_div_fixup_f32 v114, v9, v8, v114
	ds_write_b32 v5, v114 offset:4096
	s_waitcnt vmcnt(4)
	v_mul_f32_e32 v8, 0xbfb8aa3b, v115
	v_exp_f32_e32 v8, v8
	s_nop 0
	v_add_f32_e32 v8, 1.0, v8
	v_div_scale_f32 v9, s[10:11], v8, v8, v115
	v_rcp_f32_e32 v10, v9
	v_div_scale_f32 v11, vcc, v115, v8, v115
	v_fma_f32 v12, -v9, v10, 1.0
	v_fmac_f32_e32 v10, v12, v10
	v_mul_f32_e32 v12, v11, v10
	v_fma_f32 v13, -v9, v12, v11
	v_fmac_f32_e32 v12, v13, v10
	v_fma_f32 v9, -v9, v12, v11
	v_div_fmas_f32 v9, v9, v10, v12
	v_div_fixup_f32 v115, v9, v8, v115
	ds_write_b32 v5, v115 offset:6144
	s_waitcnt vmcnt(3)
	v_mul_f32_e32 v8, 0xbfb8aa3b, v116
	v_exp_f32_e32 v8, v8
	s_nop 0
	v_add_f32_e32 v8, 1.0, v8
	v_div_scale_f32 v9, s[10:11], v8, v8, v116
	v_rcp_f32_e32 v10, v9
	v_div_scale_f32 v11, vcc, v116, v8, v116
	v_fma_f32 v12, -v9, v10, 1.0
	v_fmac_f32_e32 v10, v12, v10
	v_mul_f32_e32 v12, v11, v10
	v_fma_f32 v13, -v9, v12, v11
	v_fmac_f32_e32 v12, v13, v10
	v_fma_f32 v9, -v9, v12, v11
	v_div_fmas_f32 v9, v9, v10, v12
	v_div_fixup_f32 v116, v9, v8, v116
	ds_write_b32 v5, v116 offset:8192
	s_waitcnt vmcnt(2)
	v_mul_f32_e32 v8, 0xbfb8aa3b, v117
	v_exp_f32_e32 v8, v8
	s_nop 0
	v_add_f32_e32 v8, 1.0, v8
	v_div_scale_f32 v9, s[10:11], v8, v8, v117
	v_rcp_f32_e32 v10, v9
	v_div_scale_f32 v11, vcc, v117, v8, v117
	v_fma_f32 v12, -v9, v10, 1.0
	v_fmac_f32_e32 v10, v12, v10
	v_mul_f32_e32 v12, v11, v10
	v_fma_f32 v13, -v9, v12, v11
	v_fmac_f32_e32 v12, v13, v10
	v_fma_f32 v9, -v9, v12, v11
	v_div_fmas_f32 v9, v9, v10, v12
	v_div_fixup_f32 v117, v9, v8, v117
	ds_write_b32 v5, v117 offset:10240
	s_waitcnt vmcnt(1)
	v_mul_f32_e32 v8, 0xbfb8aa3b, v118
	v_exp_f32_e32 v8, v8
	s_nop 0
	v_add_f32_e32 v8, 1.0, v8
	v_div_scale_f32 v9, s[10:11], v8, v8, v118
	v_rcp_f32_e32 v10, v9
	v_div_scale_f32 v11, vcc, v118, v8, v118
	v_fma_f32 v12, -v9, v10, 1.0
	v_fmac_f32_e32 v10, v12, v10
	v_mul_f32_e32 v12, v11, v10
	v_fma_f32 v13, -v9, v12, v11
	v_fmac_f32_e32 v12, v13, v10
	v_fma_f32 v9, -v9, v12, v11
	v_div_fmas_f32 v9, v9, v10, v12
	v_div_fixup_f32 v118, v9, v8, v118
	ds_write_b32 v5, v118 offset:12288
	s_waitcnt vmcnt(0)
	v_mul_f32_e32 v8, 0xbfb8aa3b, v119
	v_exp_f32_e32 v8, v8
	s_nop 0
	v_add_f32_e32 v8, 1.0, v8
	v_div_scale_f32 v9, s[10:11], v8, v8, v119
	v_rcp_f32_e32 v10, v9
	v_div_scale_f32 v11, vcc, v119, v8, v119
	v_fma_f32 v12, -v9, v10, 1.0
	v_fmac_f32_e32 v10, v12, v10
	v_mul_f32_e32 v12, v11, v10
	v_fma_f32 v13, -v9, v12, v11
	v_fmac_f32_e32 v12, v13, v10
	v_fma_f32 v9, -v9, v12, v11
	v_div_fmas_f32 v9, v9, v10, v12
	v_div_fixup_f32 v119, v9, v8, v119
	ds_write_b32 v5, v119 offset:14336
	v_add_u32_e32 v5, 0x4000, v5
	s_or_b64 exec, exec, s[4:5]
	s_lshl_b32 s4, s2, 6
	s_add_i32 s5, s4, 0xffffe800
	s_cmpk_lt_u32 s2, 0x60
	s_cselect_b32 s6, s4, s5
	s_cmpk_gt_u32 s2, 0x5f
	s_cselect_b64 s[8:9], -1, 0
	s_and_b64 s[10:11], s[8:9], exec
	s_load_dwordx2 s[4:5], s[0:1], 0x18
	s_mov_b32 s7, 0
	s_cselect_b32 s10, 0x400, 0
	v_lshl_add_u32 v3, v1, 7, s10
	s_lshl_b64 s[10:11], s[6:7], 2
	s_movk_i32 s13, 0x6000
	v_mov_b64_e32 v[4:5], s[10:11]
	v_mad_u64_u32 v[4:5], s[10:11], v3, s13, v[4:5]
	v_lshl_or_b32 v4, v6, 2, v4
	v_mov_b32_e32 v2, 0
	s_waitcnt lgkmcnt(0)
	v_lshl_add_u64 v[4:5], s[4:5], 0, v[4:5]
	s_mov_b64 s[4:5], 0x30000
	v_lshl_add_u64 v[8:9], v[4:5], 0, s[4:5]
	v_lshl_add_u32 v7, v1, 9, 0
	s_mov_b32 s14, 0x12000
	s_mov_b32 s15, 0xfffd6000
	s_mov_b32 s16, 0xfffdc000
	s_mov_b32 s17, 0xfffe2000
	s_mov_b32 s18, 0xfffe8000
	s_mov_b32 s19, 0xfffee000
	s_mov_b32 s22, 0xffff4000
	s_movk_i32 s23, 0xa000
	s_mov_b32 s24, 0xc000
	s_mov_b32 s25, 0x18000
	s_mov_b32 s36, 0x1e000
	s_mov_b32 s37, 0x24000
	s_mov_b32 s38, 0x2a000
	s_mov_b64 s[10:11], 0x60000
	s_mov_b32 s39, s7
	v_mov_b32_e32 v3, v2
	v_mov_b32_e32 v4, v2
	v_mov_b32_e32 v5, v2
	s_barrier

.LBB0_204:
	s_or_b64 exec, exec, s[4:5]
	v_mov_b32_e32 v2, v202
	s_waitcnt lgkmcnt(0)
	s_barrier
	s_nop 0
	s_nop 0
	s_nop 0
	s_nop 0
	s_nop 0
	s_nop 0
	s_nop 0
	s_nop 0
	s_nop 0
	s_nop 0
	s_nop 0
	s_nop 0
	s_nop 0
	s_nop 0
	s_nop 0
	s_nop 0
	s_nop 0
	s_nop 0
	s_nop 0
	s_nop 0
	s_nop 0
	s_nop 0
	s_nop 0
	s_nop 0
	s_nop 0
	s_nop 0
	s_nop 0
	s_nop 0
	s_nop 0
	s_nop 0
	s_nop 0
	s_nop 0
	s_nop 0
	s_nop 0
	s_nop 0
	s_nop 0
	s_nop 0
	s_nop 0
	v_mbcnt_lo_u32_b32 v1, -1, 0
	v_readfirstlane_b32 s4, v2
	s_ashr_i32 s4, s4, 6
	s_add_i32 s4, s4, s76
	s_cmpk_gt_i32 s4, 0x7fff
	s_cbranch_scc1 .LBB0_207
	s_load_dwordx2 s[6:7], s[0:1], 0x0
	s_load_dwordx2 s[8:9], s[0:1], 0x28
	s_add_u32 s12, s28, 0x3100000
	s_addc_u32 s13, s29, 0
	s_ashr_i32 s5, s4, 31
	s_lshl_b64 s[10:11], s[4:5], 12
	v_and_b32_e32 v21, 63, v2
	s_waitcnt lgkmcnt(0)
	s_add_u32 s10, s6, s10
	s_addc_u32 s11, s7, s11
	v_lshlrev_b32_e32 v18, 4, v21
	global_load_dwordx4 v[2:5], v18, s[10:11] offset:3072
	global_load_dwordx4 v[6:9], v18, s[10:11] offset:2048
	global_load_dwordx4 v[14:17], v18, s[10:11]
	global_load_dwordx4 v[10:13], v18, s[10:11] offset:1024
	v_mbcnt_hi_u32_b32 v25, -1, v1
	v_and_b32_e32 v24, 64, v25
	v_xor_b32_e32 v27, 1, v25
	v_add_u32_e32 v35, 64, v24
	v_xor_b32_e32 v29, 2, v25
	v_lshlrev_b32_e32 v20, 2, v21
	v_cmp_lt_i32_e32 vcc, v27, v35
	v_xor_b32_e32 v31, 4, v25
	v_or_b32_e32 v24, 0x100, v20
	v_or_b32_e32 v26, 0x200, v20
	v_or_b32_e32 v28, 0x300, v20
	v_lshlrev_b32_e32 v30, 2, v20
	v_cndmask_b32_e32 v20, v25, v27, vcc
	v_cmp_lt_i32_e32 vcc, v29, v35
	v_xor_b32_e32 v32, 8, v25
	v_xor_b32_e32 v33, 16, v25
	v_cndmask_b32_e32 v27, v25, v29, vcc
	v_cmp_lt_i32_e32 vcc, v31, v35
	v_xor_b32_e32 v34, 32, v25
	v_mov_b32_e32 v19, 0
	v_cndmask_b32_e32 v29, v25, v31, vcc
	v_cmp_lt_i32_e32 vcc, v32, v35
	v_lshlrev_b32_e32 v31, 2, v24
	s_mov_b64 s[10:11], 0x4000000
	v_cndmask_b32_e32 v37, v25, v32, vcc
	v_cmp_lt_i32_e32 vcc, v33, v35
	v_lshlrev_b32_e32 v32, 2, v26
	v_mov_b32_e32 v23, 0x358637bd
	v_cndmask_b32_e32 v38, v25, v33, vcc
	v_cmp_lt_i32_e32 vcc, v34, v35
	v_lshlrev_b32_e32 v35, 2, v27
	v_lshl_add_u64 v[26:27], s[8:9], 0, v[18:19]
	v_cndmask_b32_e32 v25, v25, v34, vcc
	v_lshlrev_b32_e32 v39, 2, v25
	v_lshl_add_u64 v[24:25], s[6:7], 0, v[18:19]
	s_lshl_b64 s[6:7], s[4:5], 11
	s_add_u32 s6, s28, s6
	v_lshlrev_b32_e32 v18, 3, v21
	s_addc_u32 s7, s29, s7
	s_ashr_i32 s37, s36, 31
	v_lshl_add_u64 v[18:19], s[6:7], 0, v[18:19]
	s_mov_b32 s14, 0x800000
	v_lshlrev_b32_e32 v33, 2, v28
	v_lshlrev_b32_e32 v34, 2, v20
	v_lshlrev_b32_e32 v36, 2, v29
	v_lshlrev_b32_e32 v37, 2, v37
	v_lshlrev_b32_e32 v38, 2, v38
	s_lshl_b64 s[6:7], s[36:37], 11
	v_lshl_add_u64 v[28:29], v[18:19], 0, s[10:11]
	s_waitcnt vmcnt(3)
	v_mov_b32_e32 v18, v2
	v_mov_b32_e32 v19, v3
	v_mov_b32_e32 v20, v4
	v_mov_b32_e32 v21, v5
	s_mov_b32 s98, -1
	global_load_dwordx4 v[104:107], v[26:27], off
	global_load_dwordx4 v[68:71], v[26:27], off offset:1024
	global_load_dwordx4 v[80:83], v[26:27], off offset:2048
	global_load_dwordx4 v[92:95], v[26:27], off offset:3072
